# strategy 4 mirrored: v054 + ONE static s_setprio 1 at entry for waves 0-3 (the leading half)
# speedup vs baseline: 1.0053x; 1.0053x over previous
_Z6mk_fwd4Args:
	v_readfirstlane_b32 s100, v0
	s_nop 3
	s_and_b32 s100, s100, 0x3ff
	s_lshr_b32 s100, s100, 6
	s_cmp_lt_u32 s100, 4
	s_cbranch_scc0 .Lprio_done
	s_setprio 1
